# v22 plus K0/K1 fragment LDS reads interleaved so each QK MFMA waits only on its own fragment (counted lgkmcnt per MFMA) in the four attention loops
# baseline (speedup 1.0000x reference)
; #define LAS __attribute__((address_space(3)))
; template <bool DIFF> ...
;     ...
;             const LAS unsigned char* kb_ = lds + buf * BUFB; const LAS unsigned char* vb_ = kb_ + KTILEB;
;             f32x16 pr[2];
;             const LAS unsigned char* vbase = vb_ + (4 * hi + ((lane & 15) >> 2)) * VROWB + (sdv + ((lane >> 4) & 1) * 16 + (lane & 3) * 4) * 2;
;     ...
;             bf16x8 vfa[NDB], vfb[NDB];
;             {
;                 bf16x8 kf[2][NS];
; #pragma unroll
;                 for (int kb = 0; kb < 2; ++kb)
; #pragma unroll
;                     for (int st = 0; st < NS; ++st) kf[kb][st] = *(const LAS bf16x8*)(kb_ + (kb * 32 + l32) * KROWB + (s * DQK + st * 16 + hi * 8) * 2);
;                 VLOAD(vfa, 0);
;                 __builtin_amdgcn_sched_barrier(0);
;                 __builtin_amdgcn_s_setprio(1);
; #pragma unroll
;                 for (int st = 0; st < NS; ++st) {
;                     pr[0] = __builtin_amdgcn_mfma_f32_32x32x16_bf16(kf[0][st], qf[st], st == 0 ? negm : pr[0], 0, 0, 0);
;                     pr[1] = __builtin_amdgcn_mfma_f32_32x32x16_bf16(kf[1][st], qf[st], st == 0 ? negm : pr[1], 0, 0, 0); }
;                 __builtin_amdgcn_s_setprio(0);
;             }
;             const int tp0 = (t == 0) ? -16 : (t - 1) * 64;
;             if (DIFF) {
;                 if (tp0 + 63 - qpos_w > -128) {
; #pragma unroll
;                     for (int kb = 0; kb < 2; ++kb)
; #pragma unroll
;                         for (int r = 0; r < 16; ++r) { const int kvi = kb * 32 + 8 * (r >> 2) + 4 * hi + (r & 3); int idx = tp0 + kvi - qpos + 128; idx = idx < 0 ? 0 : idx; pr[kb][r] += lut[idx]; }
;                 }
.Lbody_d1:
	ds_read_b128 v[80:83], v97
	ds_read_b128 v[222:225], v97 offset:8704
	ds_read_b128 v[84:87], v97 offset:32
	ds_read_b128 v[226:229], v97 offset:8736
	ds_read_b128 v[88:91], v97 offset:64
	ds_read_b128 v[230:233], v97 offset:8768
	ds_read_b128 v[92:95], v97 offset:96
	ds_read_b128 v[234:237], v97 offset:8800
	ds_read_b64_tr_b16 v[174:175], v221 offset:17408
	ds_read_b64_tr_b16 v[170:171], v221 offset:17472
	ds_read_b64_tr_b16 v[166:167], v221 offset:17536
	ds_read_b64_tr_b16 v[162:163], v221 offset:17600
	ds_read_b64_tr_b16 v[176:177], v221 offset:19968
	ds_read_b64_tr_b16 v[172:173], v221 offset:20032
	ds_read_b64_tr_b16 v[168:169], v221 offset:20096
	ds_read_b64_tr_b16 v[164:165], v221 offset:20160
	s_setprio 1
	s_waitcnt lgkmcnt(15)
	v_mfma_f32_32x32x16_bf16 v[112:127], v[80:83], v[142:145], v[64:79]
	s_waitcnt lgkmcnt(14)
	v_mfma_f32_32x32x16_bf16 v[96:111], v[222:225], v[142:145], v[64:79]
	v_add_u32_e32 v80, s47, v220
	v_ashrrev_i32_e32 v81, 31, v80
	v_add_u32_e32 v82, s47, v219
	v_lshlrev_b64 v[80:81], 11, v[80:81]
	s_waitcnt lgkmcnt(13)
	v_mfma_f32_32x32x16_bf16 v[112:127], v[84:87], v[138:141], v[112:127]
	v_ashrrev_i32_e32 v83, 31, v82
	v_lshl_add_u64 v[80:81], v[190:191], 0, v[80:81]
	v_lshlrev_b64 v[82:83], 11, v[82:83]
	v_lshl_add_u64 v[82:83], v[192:193], 0, v[82:83]
	global_load_dwordx4 v[146:149], v[80:81], off
	global_load_dwordx4 v[150:153], v[82:83], off
	s_waitcnt lgkmcnt(12)
	v_mfma_f32_32x32x16_bf16 v[96:111], v[226:229], v[138:141], v[96:111]
	v_add_u32_e32 v80, s47, v218
	v_ashrrev_i32_e32 v81, 31, v80
	v_add_u32_e32 v82, s47, v217
	v_lshlrev_b64 v[80:81], 11, v[80:81]
	s_waitcnt lgkmcnt(11)
	v_mfma_f32_32x32x16_bf16 v[112:127], v[88:91], v[134:137], v[112:127]
	v_ashrrev_i32_e32 v83, 31, v82
	v_lshl_add_u64 v[80:81], v[188:189], 0, v[80:81]
	v_lshlrev_b64 v[82:83], 11, v[82:83]
	v_lshl_add_u64 v[82:83], v[188:189], 0, v[82:83]
	global_load_dwordx4 v[154:157], v[80:81], off
	global_load_dwordx4 v[158:161], v[82:83], off
	s_waitcnt lgkmcnt(10)
	v_mfma_f32_32x32x16_bf16 v[96:111], v[230:233], v[134:137], v[96:111]
	s_waitcnt lgkmcnt(9)
	v_mfma_f32_32x32x16_bf16 v[112:127], v[92:95], v[130:133], v[112:127]
	s_waitcnt lgkmcnt(8)
	v_mfma_f32_32x32x16_bf16 v[96:111], v[234:237], v[130:133], v[96:111]
	s_setprio 0
	s_add_i32 s46, s47, 64
	s_cmp_le_i32 s46, s44
	s_cbranch_scc1 .LBB0_340
	v_add_u32_e32 v200, s47, v216
	s_add_i32 s1, 0, 0x18000
	v_max_i32_e32 v222, 0xffffff5d, v200
	v_lshl_add_u32 v223, v222, 2, s1
	v_max_i32_e32 v222, 0xffffff58, v200
	v_max_i32_e32 v228, 0xffffff4f, v200
	v_lshl_add_u32 v224, v222, 2, s1
	v_max_i32_e32 v222, 0xffffff57, v200
	v_lshl_add_u32 v229, v228, 2, s1
	v_max_i32_e32 v228, 0xffffff4e, v200
	v_lshl_add_u32 v225, v222, 2, s1
	v_max_i32_e32 v222, 0xffffff56, v200
	v_lshl_add_u32 v230, v228, 2, s1
	v_max_i32_e32 v228, 0xffffff4d, v200
	v_max_i32_e32 v80, 0xffffff80, v200
	v_max_i32_e32 v81, 0xffffff7f, v200
	v_max_i32_e32 v82, 0xffffff7e, v200
	v_max_i32_e32 v83, 0xffffff7d, v200
	v_max_i32_e32 v84, 0xffffff78, v200
	v_max_i32_e32 v85, 0xffffff77, v200
	v_max_i32_e32 v86, 0xffffff76, v200
	v_max_i32_e32 v87, 0xffffff75, v200
	v_max_i32_e32 v88, 0xffffff70, v200
	v_max_i32_e32 v89, 0xffffff6f, v200
	v_max_i32_e32 v90, 0xffffff6e, v200
	v_max_i32_e32 v91, 0xffffff6d, v200
	v_max_i32_e32 v92, 0xffffff68, v200
	v_max_i32_e32 v93, 0xffffff67, v200
	v_max_i32_e32 v94, 0xffffff66, v200
	v_max_i32_e32 v95, 0xffffff65, v200
	v_max_i32_e32 v198, 0xffffff60, v200
	v_max_i32_e32 v199, 0xffffff5f, v200
	v_max_i32_e32 v201, 0xffffff5e, v200
	v_lshl_add_u32 v226, v222, 2, s1
	v_max_i32_e32 v222, 0xffffff55, v200
	v_lshl_add_u32 v231, v228, 2, s1
	v_max_i32_e32 v228, 0xffffff48, v200
	v_lshl_add_u32 v80, v80, 2, s1
	v_lshl_add_u32 v81, v81, 2, s1
	v_lshl_add_u32 v82, v82, 2, s1
	v_lshl_add_u32 v83, v83, 2, s1
	v_lshl_add_u32 v84, v84, 2, s1
	v_lshl_add_u32 v85, v85, 2, s1
	v_lshl_add_u32 v86, v86, 2, s1
	v_lshl_add_u32 v87, v87, 2, s1
	v_lshl_add_u32 v88, v88, 2, s1
	v_lshl_add_u32 v89, v89, 2, s1
	v_lshl_add_u32 v90, v90, 2, s1
	v_lshl_add_u32 v91, v91, 2, s1
	v_lshl_add_u32 v92, v92, 2, s1
	v_lshl_add_u32 v93, v93, 2, s1
	v_lshl_add_u32 v94, v94, 2, s1
	v_lshl_add_u32 v95, v95, 2, s1
	v_lshl_add_u32 v198, v198, 2, s1
	v_lshl_add_u32 v199, v199, 2, s1
	v_lshl_add_u32 v201, v201, 2, s1
	v_lshl_add_u32 v227, v222, 2, s1
	v_lshl_add_u32 v232, v228, 2, s1
	v_max_i32_e32 v228, 0xffffff47, v200
	ds_read_b32 v80, v80 offset:512
	ds_read_b32 v81, v81 offset:516
	ds_read_b32 v82, v82 offset:520
	ds_read_b32 v83, v83 offset:524
	ds_read_b32 v84, v84 offset:544
	ds_read_b32 v85, v85 offset:548
	ds_read_b32 v86, v86 offset:552
	ds_read_b32 v87, v87 offset:556
	ds_read_b32 v88, v88 offset:576
	ds_read_b32 v89, v89 offset:580
	ds_read_b32 v90, v90 offset:584
	ds_read_b32 v91, v91 offset:588
	ds_read_b32 v92, v92 offset:608
	ds_read_b32 v93, v93 offset:612
	ds_read_b32 v94, v94 offset:616
	ds_read_b32 v95, v95 offset:620
	ds_read_b32 v198, v198 offset:640
	ds_read_b32 v199, v199 offset:644
	ds_read_b32 v222, v201 offset:648
	ds_read_b32 v223, v223 offset:652
	ds_read_b32 v224, v224 offset:672
	ds_read_b32 v225, v225 offset:676
	ds_read_b32 v226, v226 offset:680
	ds_read_b32 v227, v227 offset:684
	v_max_i32_e32 v201, 0xffffff50, v200
	v_lshl_add_u32 v233, v228, 2, s1
	v_max_i32_e32 v228, 0xffffff46, v200
	v_lshl_add_u32 v201, v201, 2, s1
	v_lshl_add_u32 v234, v228, 2, s1
	v_max_i32_e32 v200, 0xffffff45, v200
	v_lshl_add_u32 v200, v200, 2, s1
	ds_read_b32 v228, v201 offset:704
	ds_read_b32 v229, v229 offset:708
	ds_read_b32 v230, v230 offset:712
	ds_read_b32 v231, v231 offset:716
	ds_read_b32 v232, v232 offset:736
	ds_read_b32 v233, v233 offset:740
	ds_read_b32 v234, v234 offset:744
	ds_read_b32 v235, v200 offset:748
	s_waitcnt lgkmcnt(14)
	v_pk_add_f32 v[126:127], v[126:127], v[94:95]
	v_pk_add_f32 v[124:125], v[124:125], v[92:93]
	v_pk_add_f32 v[122:123], v[122:123], v[90:91]
	v_pk_add_f32 v[120:121], v[120:121], v[88:89]
	v_pk_add_f32 v[118:119], v[118:119], v[86:87]
	v_pk_add_f32 v[116:117], v[116:117], v[84:85]
	v_pk_add_f32 v[114:115], v[114:115], v[82:83]
	v_pk_add_f32 v[112:113], v[112:113], v[80:81]
	s_waitcnt lgkmcnt(0)
	v_pk_add_f32 v[110:111], v[110:111], v[234:235]
	v_pk_add_f32 v[108:109], v[108:109], v[232:233]
	v_pk_add_f32 v[106:107], v[106:107], v[230:231]
	v_pk_add_f32 v[104:105], v[104:105], v[228:229]
	v_pk_add_f32 v[102:103], v[102:103], v[226:227]
	v_pk_add_f32 v[100:101], v[100:101], v[224:225]
	v_pk_add_f32 v[98:99], v[98:99], v[222:223]
	v_pk_add_f32 v[96:97], v[96:97], v[198:199]

; #define LAS __attribute__((address_space(3)))
; template <bool DIFF> ...
;     ...
;             const LAS unsigned char* kb_ = lds + buf * BUFB; const LAS unsigned char* vb_ = kb_ + KTILEB;
;             f32x16 pr[2];
;             const LAS unsigned char* vbase = vb_ + (4 * hi + ((lane & 15) >> 2)) * VROWB + (sdv + ((lane >> 4) & 1) * 16 + (lane & 3) * 4) * 2;
;     ...
;             bf16x8 vfa[NDB], vfb[NDB];
;             {
;                 bf16x8 kf[2][NS];
; #pragma unroll
;                 for (int kb = 0; kb < 2; ++kb)
; #pragma unroll
;                     for (int st = 0; st < NS; ++st) kf[kb][st] = *(const LAS bf16x8*)(kb_ + (kb * 32 + l32) * KROWB + (s * DQK + st * 16 + hi * 8) * 2);
;                 VLOAD(vfa, 0);
;                 __builtin_amdgcn_sched_barrier(0);
;                 __builtin_amdgcn_s_setprio(1);
; #pragma unroll
;                 for (int st = 0; st < NS; ++st) {
;                     pr[0] = __builtin_amdgcn_mfma_f32_32x32x16_bf16(kf[0][st], qf[st], st == 0 ? negm : pr[0], 0, 0, 0);
;                     pr[1] = __builtin_amdgcn_mfma_f32_32x32x16_bf16(kf[1][st], qf[st], st == 0 ? negm : pr[1], 0, 0, 0); }
;                 __builtin_amdgcn_s_setprio(0);
;             }
;             const int tp0 = (t == 0) ? -16 : (t - 1) * 64;
;             if (DIFF) {
;                 if (tp0 + 63 - qpos_w > -128) {
; #pragma unroll
;                     for (int kb = 0; kb < 2; ++kb)
; #pragma unroll
;                         for (int r = 0; r < 16; ++r) { const int kvi = kb * 32 + 8 * (r >> 2) + 4 * hi + (r & 3); int idx = tp0 + kvi - qpos + 128; idx = idx < 0 ? 0 : idx; pr[kb][r] += lut[idx]; }
;                 }
.Lbody_d2:
	ds_read_b128 v[80:83], v97
	ds_read_b128 v[222:225], v97 offset:8704
	ds_read_b128 v[84:87], v97 offset:32
	ds_read_b128 v[226:229], v97 offset:8736
	ds_read_b128 v[88:91], v97 offset:64
	ds_read_b128 v[230:233], v97 offset:8768
	ds_read_b128 v[92:95], v97 offset:96
	ds_read_b128 v[234:237], v97 offset:8800
	ds_read_b64_tr_b16 v[174:175], v221 offset:17408
	ds_read_b64_tr_b16 v[170:171], v221 offset:17472
	ds_read_b64_tr_b16 v[166:167], v221 offset:17536
	ds_read_b64_tr_b16 v[162:163], v221 offset:17600
	ds_read_b64_tr_b16 v[176:177], v221 offset:19968
	ds_read_b64_tr_b16 v[172:173], v221 offset:20032
	ds_read_b64_tr_b16 v[168:169], v221 offset:20096
	ds_read_b64_tr_b16 v[164:165], v221 offset:20160
	s_setprio 1
	s_waitcnt lgkmcnt(15)
	v_mfma_f32_32x32x16_bf16 v[112:127], v[80:83], v[142:145], v[64:79]
	s_waitcnt lgkmcnt(14)
	v_mfma_f32_32x32x16_bf16 v[96:111], v[222:225], v[142:145], v[64:79]
	v_add_u32_e32 v80, s35, v220
	v_ashrrev_i32_e32 v81, 31, v80
	v_add_u32_e32 v82, s35, v219
	v_lshlrev_b64 v[80:81], 11, v[80:81]
	s_waitcnt lgkmcnt(13)
	v_mfma_f32_32x32x16_bf16 v[112:127], v[84:87], v[138:141], v[112:127]
	v_ashrrev_i32_e32 v83, 31, v82
	v_lshl_add_u64 v[80:81], v[190:191], 0, v[80:81]
	v_lshlrev_b64 v[82:83], 11, v[82:83]
	v_lshl_add_u64 v[82:83], v[192:193], 0, v[82:83]
	global_load_dwordx4 v[146:149], v[80:81], off
	global_load_dwordx4 v[150:153], v[82:83], off
	s_waitcnt lgkmcnt(12)
	v_mfma_f32_32x32x16_bf16 v[96:111], v[226:229], v[138:141], v[96:111]
	v_add_u32_e32 v80, s35, v218
	v_ashrrev_i32_e32 v81, 31, v80
	v_add_u32_e32 v82, s35, v217
	v_lshlrev_b64 v[80:81], 11, v[80:81]
	s_waitcnt lgkmcnt(11)
	v_mfma_f32_32x32x16_bf16 v[112:127], v[88:91], v[134:137], v[112:127]
	v_ashrrev_i32_e32 v83, 31, v82
	v_lshl_add_u64 v[80:81], v[188:189], 0, v[80:81]
	v_lshlrev_b64 v[82:83], 11, v[82:83]
	v_lshl_add_u64 v[82:83], v[188:189], 0, v[82:83]
	global_load_dwordx4 v[154:157], v[80:81], off
	global_load_dwordx4 v[158:161], v[82:83], off
	s_waitcnt lgkmcnt(10)
	v_mfma_f32_32x32x16_bf16 v[96:111], v[230:233], v[134:137], v[96:111]
	s_waitcnt lgkmcnt(9)
	v_mfma_f32_32x32x16_bf16 v[112:127], v[92:95], v[130:133], v[112:127]
	s_waitcnt lgkmcnt(8)
	v_mfma_f32_32x32x16_bf16 v[96:111], v[234:237], v[130:133], v[96:111]
	s_setprio 0
	s_add_i32 s20, s35, 64
	s_cmp_le_u32 s20, s30
	s_cbranch_scc1 .LBB0_365
	v_add_u32_e32 v200, s35, v216
	s_add_i32 s1, 0, 0x18000
	v_max_i32_e32 v222, 0xffffff5d, v200
	v_lshl_add_u32 v223, v222, 2, s1
	v_max_i32_e32 v222, 0xffffff58, v200
	v_max_i32_e32 v228, 0xffffff4f, v200
	v_lshl_add_u32 v224, v222, 2, s1
	v_max_i32_e32 v222, 0xffffff57, v200
	v_lshl_add_u32 v229, v228, 2, s1
	v_max_i32_e32 v228, 0xffffff4e, v200
	v_lshl_add_u32 v225, v222, 2, s1
	v_max_i32_e32 v222, 0xffffff56, v200
	v_lshl_add_u32 v230, v228, 2, s1
	v_max_i32_e32 v228, 0xffffff4d, v200
	v_max_i32_e32 v80, 0xffffff80, v200
	v_max_i32_e32 v81, 0xffffff7f, v200
	v_max_i32_e32 v82, 0xffffff7e, v200
	v_max_i32_e32 v83, 0xffffff7d, v200
	v_max_i32_e32 v84, 0xffffff78, v200
	v_max_i32_e32 v85, 0xffffff77, v200
	v_max_i32_e32 v86, 0xffffff76, v200
	v_max_i32_e32 v87, 0xffffff75, v200
	v_max_i32_e32 v88, 0xffffff70, v200
	v_max_i32_e32 v89, 0xffffff6f, v200
	v_max_i32_e32 v90, 0xffffff6e, v200
	v_max_i32_e32 v91, 0xffffff6d, v200
	v_max_i32_e32 v92, 0xffffff68, v200
	v_max_i32_e32 v93, 0xffffff67, v200
	v_max_i32_e32 v94, 0xffffff66, v200
	v_max_i32_e32 v95, 0xffffff65, v200
	v_max_i32_e32 v198, 0xffffff60, v200
	v_max_i32_e32 v199, 0xffffff5f, v200
	v_max_i32_e32 v201, 0xffffff5e, v200
	v_lshl_add_u32 v226, v222, 2, s1
	v_max_i32_e32 v222, 0xffffff55, v200
	v_lshl_add_u32 v231, v228, 2, s1
	v_max_i32_e32 v228, 0xffffff48, v200
	v_lshl_add_u32 v80, v80, 2, s1
	v_lshl_add_u32 v81, v81, 2, s1
	v_lshl_add_u32 v82, v82, 2, s1
	v_lshl_add_u32 v83, v83, 2, s1
	v_lshl_add_u32 v84, v84, 2, s1
	v_lshl_add_u32 v85, v85, 2, s1
	v_lshl_add_u32 v86, v86, 2, s1
	v_lshl_add_u32 v87, v87, 2, s1
	v_lshl_add_u32 v88, v88, 2, s1
	v_lshl_add_u32 v89, v89, 2, s1
	v_lshl_add_u32 v90, v90, 2, s1
	v_lshl_add_u32 v91, v91, 2, s1
	v_lshl_add_u32 v92, v92, 2, s1
	v_lshl_add_u32 v93, v93, 2, s1
	v_lshl_add_u32 v94, v94, 2, s1
	v_lshl_add_u32 v95, v95, 2, s1
	v_lshl_add_u32 v198, v198, 2, s1
	v_lshl_add_u32 v199, v199, 2, s1
	v_lshl_add_u32 v201, v201, 2, s1
	v_lshl_add_u32 v227, v222, 2, s1
	v_lshl_add_u32 v232, v228, 2, s1
	v_max_i32_e32 v228, 0xffffff47, v200
	ds_read_b32 v80, v80 offset:512
	ds_read_b32 v81, v81 offset:516
	ds_read_b32 v82, v82 offset:520
	ds_read_b32 v83, v83 offset:524
	ds_read_b32 v84, v84 offset:544
	ds_read_b32 v85, v85 offset:548
	ds_read_b32 v86, v86 offset:552
	ds_read_b32 v87, v87 offset:556
	ds_read_b32 v88, v88 offset:576
	ds_read_b32 v89, v89 offset:580
	ds_read_b32 v90, v90 offset:584
	ds_read_b32 v91, v91 offset:588
	ds_read_b32 v92, v92 offset:608
	ds_read_b32 v93, v93 offset:612
	ds_read_b32 v94, v94 offset:616
	ds_read_b32 v95, v95 offset:620
	ds_read_b32 v198, v198 offset:640
	ds_read_b32 v199, v199 offset:644
	ds_read_b32 v222, v201 offset:648
	ds_read_b32 v223, v223 offset:652
	ds_read_b32 v224, v224 offset:672
	ds_read_b32 v225, v225 offset:676
	ds_read_b32 v226, v226 offset:680
	ds_read_b32 v227, v227 offset:684
	v_max_i32_e32 v201, 0xffffff50, v200
	v_lshl_add_u32 v233, v228, 2, s1
	v_max_i32_e32 v228, 0xffffff46, v200
	v_lshl_add_u32 v201, v201, 2, s1
	v_lshl_add_u32 v234, v228, 2, s1
	v_max_i32_e32 v200, 0xffffff45, v200
	v_lshl_add_u32 v200, v200, 2, s1
	ds_read_b32 v228, v201 offset:704
	ds_read_b32 v229, v229 offset:708
	ds_read_b32 v230, v230 offset:712
	ds_read_b32 v231, v231 offset:716
	ds_read_b32 v232, v232 offset:736
	ds_read_b32 v233, v233 offset:740
	ds_read_b32 v234, v234 offset:744
	ds_read_b32 v235, v200 offset:748
	s_waitcnt lgkmcnt(14)
	v_pk_add_f32 v[126:127], v[126:127], v[94:95]
	v_pk_add_f32 v[124:125], v[124:125], v[92:93]
	v_pk_add_f32 v[122:123], v[122:123], v[90:91]
	v_pk_add_f32 v[120:121], v[120:121], v[88:89]
	v_pk_add_f32 v[118:119], v[118:119], v[86:87]
	v_pk_add_f32 v[116:117], v[116:117], v[84:85]
	v_pk_add_f32 v[114:115], v[114:115], v[82:83]
	v_pk_add_f32 v[112:113], v[112:113], v[80:81]
	s_waitcnt lgkmcnt(0)
	v_pk_add_f32 v[110:111], v[110:111], v[234:235]
	v_pk_add_f32 v[108:109], v[108:109], v[232:233]
	v_pk_add_f32 v[106:107], v[106:107], v[230:231]
	v_pk_add_f32 v[104:105], v[104:105], v[228:229]
	v_pk_add_f32 v[102:103], v[102:103], v[226:227]
	v_pk_add_f32 v[100:101], v[100:101], v[224:225]
	v_pk_add_f32 v[98:99], v[98:99], v[222:223]
	v_pk_add_f32 v[96:97], v[96:97], v[198:199]

; template <bool DIFF> ...
;     ...
;             const LAS unsigned char* kb_ = lds + buf * BUFB; const LAS unsigned char* vb_ = kb_ + KTILEB;
;             f32x16 pr[2];
;             const LAS unsigned char* vbase = vb_ + (4 * hi + ((lane & 15) >> 2)) * VROWB + (sdv + ((lane >> 4) & 1) * 16 + (lane & 3) * 4) * 2;
;     ...
;             bf16x8 vfa[NDB], vfb[NDB];
;             {
;                 bf16x8 kf[2][NS];
; #pragma unroll
;                 for (int kb = 0; kb < 2; ++kb)
; #pragma unroll
;                     for (int st = 0; st < NS; ++st) kf[kb][st] = *(const LAS bf16x8*)(kb_ + (kb * 32 + l32) * KROWB + (s * DQK + st * 16 + hi * 8) * 2);
;                 VLOAD(vfa, 0);
;                 __builtin_amdgcn_sched_barrier(0);
;                 __builtin_amdgcn_s_setprio(1);
; #pragma unroll
;                 for (int st = 0; st < NS; ++st) {
;                     pr[0] = __builtin_amdgcn_mfma_f32_32x32x16_bf16(kf[0][st], qf[st], st == 0 ? negm : pr[0], 0, 0, 0);
;                     pr[1] = __builtin_amdgcn_mfma_f32_32x32x16_bf16(kf[1][st], qf[st], st == 0 ? negm : pr[1], 0, 0, 0); }
;                 __builtin_amdgcn_s_setprio(0);
;             }
;             const int tp0 = (t == 0) ? -16 : (t - 1) * 64;
;             if (DIFF) {
;                 if (tp0 + 63 - qpos_w > -128) {
; #pragma unroll
;                     for (int kb = 0; kb < 2; ++kb)
; #pragma unroll
;                         for (int r = 0; r < 16; ++r) { const int kvi = kb * 32 + 8 * (r >> 2) + 4 * hi + (r & 3); int idx = tp0 + kvi - qpos + 128; idx = idx < 0 ? 0 : idx; pr[kb][r] += lut[idx]; }
;                 }
;             }
;             const int nval = (t == 0) ? 16 : (t == NT - 1 ? lastv : 64);
;             if (nval < 64) {
; #pragma unroll
;                 for (int kb = 0; kb < 2; ++kb)
; #pragma unroll
;                     for (int r = 0; r < 16; ++r) { const int kvi = kb * 32 + 8 * (r >> 2) + 4 * hi + (r & 3); if (kvi >= nval) pr[kb][r] = -INFINITY; }
;             }
;             float mx;
;             { float a0 = fmaxf(fmaxf(pr[0][0], pr[0][1]), pr[0][2]), a1 = fmaxf(fmaxf(pr[1][0], pr[1][1]), pr[1][2]);
; #pragma unroll
;               for (int r = 3; r < 15; r += 2) { a0 = fmaxf(fmaxf(a0, pr[0][r]), pr[0][r + 1]); a1 = fmaxf(fmaxf(a1, pr[1][r]), pr[1][r + 1]); }
;               mx = fmaxf(fmaxf(a0, a1), fmaxf(pr[0][15], pr[1][15])); }
.LBB0_697:
	s_and_b32 s40, s38, 1
	s_cmp_ge_u32 s38, s35
	s_cbranch_scc1 .LBB0_695
	s_mul_i32 s41, s40, 0xb400
	s_add_i32 s41, s41, 0
	v_add3_u32 v65, s41, v175, v174
	ds_read_b128 v[48:51], v65
	ds_read_b128 v[202:205], v65 offset:12800
	ds_read_b128 v[52:55], v65 offset:32
	ds_read_b128 v[206:209], v65 offset:12832
	ds_read_b128 v[56:59], v65 offset:64
	ds_read_b128 v[210:213], v65 offset:12864
	ds_read_b128 v[60:63], v65 offset:96
	ds_read_b128 v[214:217], v65 offset:12896
	ds_read_b128 v[186:189], v65 offset:128
	ds_read_b128 v[218:221], v65 offset:12928
	ds_read_b128 v[190:193], v65 offset:160
	ds_read_b128 v[222:225], v65 offset:12960
	v_add_u32_e32 v64, s41, v173
	v_add_u32_e32 v185, v64, v172
	ds_read_b64_tr_b16 v[142:143], v185 offset:25600
	ds_read_b64_tr_b16 v[144:145], v185 offset:28160
	ds_read_b64_tr_b16 v[148:149], v185 offset:28224
	ds_read_b64_tr_b16 v[146:147], v185 offset:25664
	s_setprio 1
	s_waitcnt lgkmcnt(15)
	v_mfma_f32_32x32x16_bf16 v[80:95], v[48:51], v[116:119], v[32:47]
	s_waitcnt lgkmcnt(14)
	v_mfma_f32_32x32x16_bf16 v[64:79], v[202:205], v[116:119], v[32:47]
	v_add_u32_e32 v48, s39, v184
	v_add_u32_e32 v50, s39, v183
	v_mad_i64_i32 v[48:49], s[40:41], v48, s2, v[156:157]
	v_mad_i64_i32 v[50:51], s[40:41], v50, s2, v[158:159]
	s_waitcnt lgkmcnt(13)
	v_mfma_f32_32x32x16_bf16 v[80:95], v[52:55], v[112:115], v[80:95]
	global_load_dwordx4 v[124:127], v[48:49], off
	global_load_dwordx4 v[120:123], v[50:51], off
	s_waitcnt lgkmcnt(12)
	v_mfma_f32_32x32x16_bf16 v[64:79], v[206:209], v[112:115], v[64:79]
	v_add_u32_e32 v50, s39, v177
	v_add_u32_e32 v48, s39, v182
	v_ashrrev_i32_e32 v51, 31, v50
	s_waitcnt lgkmcnt(11)
	v_mfma_f32_32x32x16_bf16 v[80:95], v[56:59], v[108:111], v[80:95]
	v_mad_i64_i32 v[48:49], s[40:41], v48, s2, v[160:161]
	v_lshlrev_b64 v[50:51], 10, v[50:51]
	v_lshl_add_u64 v[50:51], v[154:155], 0, v[50:51]
	s_waitcnt lgkmcnt(10)
	v_mfma_f32_32x32x16_bf16 v[64:79], v[210:213], v[108:111], v[64:79]
	global_load_dwordx4 v[134:137], v[48:49], off
	global_load_dwordx4 v[130:133], v[50:51], off
	s_waitcnt lgkmcnt(9)
	v_mfma_f32_32x32x16_bf16 v[80:95], v[60:63], v[104:107], v[80:95]
	v_add_u32_e32 v48, s39, v176
	v_ashrrev_i32_e32 v49, 31, v48
	v_lshlrev_b64 v[48:49], 10, v[48:49]
	v_lshl_add_u64 v[48:49], v[154:155], 0, v[48:49]
	s_waitcnt lgkmcnt(8)
	v_mfma_f32_32x32x16_bf16 v[64:79], v[214:217], v[104:107], v[64:79]
	global_load_dwordx4 v[138:141], v[48:49], off
	s_and_b32 s40, s38, 1
	s_waitcnt lgkmcnt(7)
	v_mfma_f32_32x32x16_bf16 v[80:95], v[186:189], v[100:103], v[80:95]
	s_waitcnt lgkmcnt(6)
	v_mfma_f32_32x32x16_bf16 v[64:79], v[218:221], v[100:103], v[64:79]
	s_waitcnt lgkmcnt(5)
	v_mfma_f32_32x32x16_bf16 v[80:95], v[190:193], v[96:99], v[80:95]
	s_waitcnt lgkmcnt(4)
	v_mfma_f32_32x32x16_bf16 v[64:79], v[222:225], v[96:99], v[64:79]
	s_setprio 0
	ds_read_b64_tr_b16 v[202:203], v185 offset:30720
	ds_read_b64_tr_b16 v[204:205], v185 offset:33280
	ds_read_b64_tr_b16 v[206:207], v185 offset:30784
	ds_read_b64_tr_b16 v[208:209], v185 offset:33344
	s_nop 4
	v_max3_f32 v48, v80, v81, v82
	s_nop 0
	v_max3_f32 v49, v64, v65, v66
	v_max3_f32 v48, v48, v83, v84
	v_max3_f32 v49, v49, v67, v68
	v_max3_f32 v48, v48, v85, v86
	v_max3_f32 v49, v49, v69, v70
	v_max3_f32 v48, v48, v87, v88
	v_max3_f32 v49, v49, v71, v72
	v_max3_f32 v48, v48, v89, v90
	v_max3_f32 v49, v49, v73, v74
	v_max3_f32 v48, v48, v91, v92
	v_max3_f32 v49, v49, v75, v76
	v_max_f32_e32 v50, v79, v79
	v_max_f32_e32 v51, v95, v95
	v_max3_f32 v48, v48, v93, v94
	v_max3_f32 v49, v49, v77, v78
	v_max_f32_e32 v50, v51, v50
	v_max3_f32 v48, v48, v49, v50
	v_cmp_lt_f32_e32 vcc, s33, v48
	s_cbranch_vccz .LBB0_700
	ds_bpermute_b32 v49, v163, v48
	s_waitcnt lgkmcnt(0)
	v_max_f32_e32 v49, v49, v49
	v_max_f32_e32 v48, v48, v49
	v_max_f32_e32 v32, v48, v48
	v_max_f32_e32 v33, 0, v32
	v_exp_f32_e64 v34, -v33
	v_add_f32_e32 v152, v152, v33
	v_xor_b32_e32 v32, 0x80000000, v152
	v_sub_f32_e32 v80, v80, v33
	v_sub_f32_e32 v81, v81, v33
	v_sub_f32_e32 v82, v82, v33
	v_sub_f32_e32 v95, v95, v33
	v_sub_f32_e32 v83, v83, v33
	v_sub_f32_e32 v84, v84, v33
	v_sub_f32_e32 v85, v85, v33
	v_sub_f32_e32 v86, v86, v33
	v_sub_f32_e32 v87, v87, v33
	v_sub_f32_e32 v88, v88, v33
	v_sub_f32_e32 v89, v89, v33
	v_sub_f32_e32 v90, v90, v33
	v_sub_f32_e32 v91, v91, v33
	v_sub_f32_e32 v92, v92, v33
	v_sub_f32_e32 v93, v93, v33
	v_sub_f32_e32 v94, v94, v33
	v_sub_f32_e32 v64, v64, v33
	v_sub_f32_e32 v65, v65, v33
	v_sub_f32_e32 v66, v66, v33
	v_sub_f32_e32 v67, v67, v33
	v_sub_f32_e32 v68, v68, v33
	v_sub_f32_e32 v69, v69, v33
	v_sub_f32_e32 v70, v70, v33
	v_sub_f32_e32 v71, v71, v33
	v_sub_f32_e32 v72, v72, v33
	v_sub_f32_e32 v73, v73, v33
	v_sub_f32_e32 v74, v74, v33
	v_sub_f32_e32 v75, v75, v33
	v_sub_f32_e32 v76, v76, v33
	v_sub_f32_e32 v77, v77, v33
	v_sub_f32_e32 v78, v78, v33
	v_sub_f32_e32 v79, v79, v33
	v_pk_mul_f32 v[30:31], v[30:31], v[34:35] op_sel_hi:[1,0]
	v_pk_mul_f32 v[28:29], v[28:29], v[34:35] op_sel_hi:[1,0]
	v_pk_mul_f32 v[26:27], v[26:27], v[34:35] op_sel_hi:[1,0]
	v_pk_mul_f32 v[24:25], v[24:25], v[34:35] op_sel_hi:[1,0]
	v_pk_mul_f32 v[22:23], v[22:23], v[34:35] op_sel_hi:[1,0]
	v_pk_mul_f32 v[20:21], v[20:21], v[34:35] op_sel_hi:[1,0]
	v_pk_mul_f32 v[18:19], v[18:19], v[34:35] op_sel_hi:[1,0]
	v_pk_mul_f32 v[16:17], v[16:17], v[34:35] op_sel_hi:[1,0]
	v_pk_mul_f32 v[14:15], v[14:15], v[34:35] op_sel_hi:[1,0]
	v_pk_mul_f32 v[12:13], v[12:13], v[34:35] op_sel_hi:[1,0]
	v_pk_mul_f32 v[10:11], v[10:11], v[34:35] op_sel_hi:[1,0]
	v_pk_mul_f32 v[8:9], v[8:9], v[34:35] op_sel_hi:[1,0]
	v_pk_mul_f32 v[6:7], v[6:7], v[34:35] op_sel_hi:[1,0]
	v_pk_mul_f32 v[4:5], v[4:5], v[34:35] op_sel_hi:[1,0]
	v_pk_mul_f32 v[2:3], v[2:3], v[34:35] op_sel_hi:[1,0]
	v_pk_mul_f32 v[0:1], v[0:1], v[34:35] op_sel_hi:[1,0]
	v_mul_f32_e32 v153, v153, v34
	v_mov_b32_e32 v33, v32
	v_mov_b32_e32 v34, v32
	v_mov_b32_e32 v35, v32
	v_mov_b32_e32 v36, v32
	v_mov_b32_e32 v37, v32
	v_mov_b32_e32 v38, v32
	v_mov_b32_e32 v39, v32
	v_mov_b32_e32 v40, v32
	v_mov_b32_e32 v41, v32
	v_mov_b32_e32 v42, v32
	v_mov_b32_e32 v43, v32
	v_mov_b32_e32 v44, v32
	v_mov_b32_e32 v45, v32
	v_mov_b32_e32 v46, v32
	v_mov_b32_e32 v47, v32
	s_branch .LBB0_701

; template <bool DIFF> ...
;     ...
;             const LAS unsigned char* kb_ = lds + buf * BUFB; const LAS unsigned char* vb_ = kb_ + KTILEB;
;             f32x16 pr[2];
;             const LAS unsigned char* vbase = vb_ + (4 * hi + ((lane & 15) >> 2)) * VROWB + (sdv + ((lane >> 4) & 1) * 16 + (lane & 3) * 4) * 2;
;     ...
;             bf16x8 vfa[NDB], vfb[NDB];
;             {
;                 bf16x8 kf[2][NS];
; #pragma unroll
;                 for (int kb = 0; kb < 2; ++kb)
; #pragma unroll
;                     for (int st = 0; st < NS; ++st) kf[kb][st] = *(const LAS bf16x8*)(kb_ + (kb * 32 + l32) * KROWB + (s * DQK + st * 16 + hi * 8) * 2);
;                 VLOAD(vfa, 0);
;                 __builtin_amdgcn_sched_barrier(0);
;                 __builtin_amdgcn_s_setprio(1);
; #pragma unroll
;                 for (int st = 0; st < NS; ++st) {
;                     pr[0] = __builtin_amdgcn_mfma_f32_32x32x16_bf16(kf[0][st], qf[st], st == 0 ? negm : pr[0], 0, 0, 0);
;                     pr[1] = __builtin_amdgcn_mfma_f32_32x32x16_bf16(kf[1][st], qf[st], st == 0 ? negm : pr[1], 0, 0, 0); }
;                 __builtin_amdgcn_s_setprio(0);
;             }
;             const int tp0 = (t == 0) ? -16 : (t - 1) * 64;
;             if (DIFF) {
;                 if (tp0 + 63 - qpos_w > -128) {
; #pragma unroll
;                     for (int kb = 0; kb < 2; ++kb)
; #pragma unroll
;                         for (int r = 0; r < 16; ++r) { const int kvi = kb * 32 + 8 * (r >> 2) + 4 * hi + (r & 3); int idx = tp0 + kvi - qpos + 128; idx = idx < 0 ? 0 : idx; pr[kb][r] += lut[idx]; }
;                 }
;             }
;             const int nval = (t == 0) ? 16 : (t == NT - 1 ? lastv : 64);
;             if (nval < 64) {
; #pragma unroll
;                 for (int kb = 0; kb < 2; ++kb)
; #pragma unroll
;                     for (int r = 0; r < 16; ++r) { const int kvi = kb * 32 + 8 * (r >> 2) + 4 * hi + (r & 3); if (kvi >= nval) pr[kb][r] = -INFINITY; }
;             }
;             float mx;
;             { float a0 = fmaxf(fmaxf(pr[0][0], pr[0][1]), pr[0][2]), a1 = fmaxf(fmaxf(pr[1][0], pr[1][1]), pr[1][2]);
; #pragma unroll
;               for (int r = 3; r < 15; r += 2) { a0 = fmaxf(fmaxf(a0, pr[0][r]), pr[0][r + 1]); a1 = fmaxf(fmaxf(a1, pr[1][r]), pr[1][r + 1]); }
;               mx = fmaxf(fmaxf(a0, a1), fmaxf(pr[0][15], pr[1][15])); }
.LBB0_709:
	s_and_b32 s1, s18, 1
	s_cmp_ge_u32 s18, s19
	s_cbranch_scc1 .LBB0_707
	s_mul_i32 s16, s1, 0xb400
	s_add_i32 s16, s16, 0
	v_add3_u32 v65, s16, v175, v174
	ds_read_b128 v[48:51], v65
	ds_read_b128 v[202:205], v65 offset:12800
	ds_read_b128 v[52:55], v65 offset:32
	ds_read_b128 v[206:209], v65 offset:12832
	ds_read_b128 v[56:59], v65 offset:64
	ds_read_b128 v[210:213], v65 offset:12864
	ds_read_b128 v[60:63], v65 offset:96
	ds_read_b128 v[214:217], v65 offset:12896
	ds_read_b128 v[186:189], v65 offset:128
	ds_read_b128 v[218:221], v65 offset:12928
	ds_read_b128 v[190:193], v65 offset:160
	ds_read_b128 v[222:225], v65 offset:12960
	v_add_u32_e32 v64, s16, v173
	v_add_u32_e32 v185, v64, v172
	ds_read_b64_tr_b16 v[142:143], v185 offset:25600
	ds_read_b64_tr_b16 v[144:145], v185 offset:28160
	ds_read_b64_tr_b16 v[148:149], v185 offset:28224
	ds_read_b64_tr_b16 v[146:147], v185 offset:25664
	s_setprio 1
	s_waitcnt lgkmcnt(15)
	v_mfma_f32_32x32x16_bf16 v[80:95], v[48:51], v[116:119], v[32:47]
	s_waitcnt lgkmcnt(14)
	v_mfma_f32_32x32x16_bf16 v[64:79], v[202:205], v[116:119], v[32:47]
	v_add_u32_e32 v48, s20, v184
	v_add_u32_e32 v50, s20, v183
	v_mad_i64_i32 v[48:49], s[22:23], v48, s2, v[156:157]
	v_mad_i64_i32 v[50:51], s[22:23], v50, s2, v[158:159]
	s_waitcnt lgkmcnt(13)
	v_mfma_f32_32x32x16_bf16 v[80:95], v[52:55], v[112:115], v[80:95]
	global_load_dwordx4 v[124:127], v[48:49], off
	global_load_dwordx4 v[120:123], v[50:51], off
	s_waitcnt lgkmcnt(12)
	v_mfma_f32_32x32x16_bf16 v[64:79], v[206:209], v[112:115], v[64:79]
	v_add_u32_e32 v50, s20, v177
	v_add_u32_e32 v48, s20, v182
	v_ashrrev_i32_e32 v51, 31, v50
	s_waitcnt lgkmcnt(11)
	v_mfma_f32_32x32x16_bf16 v[80:95], v[56:59], v[108:111], v[80:95]
	v_mad_i64_i32 v[48:49], s[22:23], v48, s2, v[160:161]
	v_lshlrev_b64 v[50:51], 10, v[50:51]
	v_lshl_add_u64 v[50:51], v[154:155], 0, v[50:51]
	s_waitcnt lgkmcnt(10)
	v_mfma_f32_32x32x16_bf16 v[64:79], v[210:213], v[108:111], v[64:79]
	global_load_dwordx4 v[134:137], v[48:49], off
	global_load_dwordx4 v[130:133], v[50:51], off
	s_waitcnt lgkmcnt(9)
	v_mfma_f32_32x32x16_bf16 v[80:95], v[60:63], v[104:107], v[80:95]
	v_add_u32_e32 v48, s20, v176
	v_ashrrev_i32_e32 v49, 31, v48
	v_lshlrev_b64 v[48:49], 10, v[48:49]
	v_lshl_add_u64 v[48:49], v[154:155], 0, v[48:49]
	s_waitcnt lgkmcnt(8)
	v_mfma_f32_32x32x16_bf16 v[64:79], v[214:217], v[104:107], v[64:79]
	global_load_dwordx4 v[138:141], v[48:49], off
	s_waitcnt lgkmcnt(7)
	v_mfma_f32_32x32x16_bf16 v[80:95], v[186:189], v[100:103], v[80:95]
	s_waitcnt lgkmcnt(6)
	v_mfma_f32_32x32x16_bf16 v[64:79], v[218:221], v[100:103], v[64:79]
	s_waitcnt lgkmcnt(5)
	v_mfma_f32_32x32x16_bf16 v[80:95], v[190:193], v[96:99], v[80:95]
	s_waitcnt lgkmcnt(4)
	v_mfma_f32_32x32x16_bf16 v[64:79], v[222:225], v[96:99], v[64:79]
	s_setprio 0
	ds_read_b64_tr_b16 v[202:203], v185 offset:30720
	ds_read_b64_tr_b16 v[204:205], v185 offset:33280
	ds_read_b64_tr_b16 v[206:207], v185 offset:30784
	ds_read_b64_tr_b16 v[208:209], v185 offset:33344
	s_nop 4
	v_max3_f32 v48, v80, v81, v82
	s_nop 0
	v_max3_f32 v49, v64, v65, v66
	v_max3_f32 v48, v48, v83, v84
	v_max3_f32 v49, v49, v67, v68
	v_max3_f32 v48, v48, v85, v86
	v_max3_f32 v49, v49, v69, v70
	v_max3_f32 v48, v48, v87, v88
	v_max3_f32 v49, v49, v71, v72
	v_max3_f32 v48, v48, v89, v90
	v_max3_f32 v49, v49, v73, v74
	v_max3_f32 v48, v48, v91, v92
	v_max3_f32 v49, v49, v75, v76
	v_max_f32_e32 v50, v79, v79
	v_max_f32_e32 v51, v95, v95
	v_max3_f32 v48, v48, v93, v94
	v_max3_f32 v49, v49, v77, v78
	v_max_f32_e32 v50, v51, v50
	v_max3_f32 v48, v48, v49, v50
	v_cmp_lt_f32_e32 vcc, s33, v48
	s_cbranch_vccz .LBB0_712
	ds_bpermute_b32 v49, v163, v48
	s_waitcnt lgkmcnt(0)
	v_max_f32_e32 v49, v49, v49
	v_max_f32_e32 v48, v48, v49
	v_max_f32_e32 v32, v48, v48
	v_max_f32_e32 v33, 0, v32
	v_exp_f32_e64 v34, -v33
	v_add_f32_e32 v152, v152, v33
	v_xor_b32_e32 v32, 0x80000000, v152
	v_sub_f32_e32 v80, v80, v33
	v_sub_f32_e32 v81, v81, v33
	v_sub_f32_e32 v82, v82, v33
	v_sub_f32_e32 v95, v95, v33
	v_sub_f32_e32 v83, v83, v33
	v_sub_f32_e32 v84, v84, v33
	v_sub_f32_e32 v85, v85, v33
	v_sub_f32_e32 v86, v86, v33
	v_sub_f32_e32 v87, v87, v33
	v_sub_f32_e32 v88, v88, v33
	v_sub_f32_e32 v89, v89, v33
	v_sub_f32_e32 v90, v90, v33
	v_sub_f32_e32 v91, v91, v33
	v_sub_f32_e32 v92, v92, v33
	v_sub_f32_e32 v93, v93, v33
	v_sub_f32_e32 v94, v94, v33
	v_sub_f32_e32 v64, v64, v33
	v_sub_f32_e32 v65, v65, v33
	v_sub_f32_e32 v66, v66, v33
	v_sub_f32_e32 v67, v67, v33
	v_sub_f32_e32 v68, v68, v33
	v_sub_f32_e32 v69, v69, v33
	v_sub_f32_e32 v70, v70, v33
	v_sub_f32_e32 v71, v71, v33
	v_sub_f32_e32 v72, v72, v33
	v_sub_f32_e32 v73, v73, v33
	v_sub_f32_e32 v74, v74, v33
	v_sub_f32_e32 v75, v75, v33
	v_sub_f32_e32 v76, v76, v33
	v_sub_f32_e32 v77, v77, v33
	v_sub_f32_e32 v78, v78, v33
	v_sub_f32_e32 v79, v79, v33
	v_pk_mul_f32 v[30:31], v[30:31], v[34:35] op_sel_hi:[1,0]
	v_pk_mul_f32 v[28:29], v[28:29], v[34:35] op_sel_hi:[1,0]
	v_pk_mul_f32 v[26:27], v[26:27], v[34:35] op_sel_hi:[1,0]
	v_pk_mul_f32 v[24:25], v[24:25], v[34:35] op_sel_hi:[1,0]
	v_pk_mul_f32 v[22:23], v[22:23], v[34:35] op_sel_hi:[1,0]
	v_pk_mul_f32 v[20:21], v[20:21], v[34:35] op_sel_hi:[1,0]
	v_pk_mul_f32 v[18:19], v[18:19], v[34:35] op_sel_hi:[1,0]
	v_pk_mul_f32 v[16:17], v[16:17], v[34:35] op_sel_hi:[1,0]
	v_pk_mul_f32 v[14:15], v[14:15], v[34:35] op_sel_hi:[1,0]
	v_pk_mul_f32 v[12:13], v[12:13], v[34:35] op_sel_hi:[1,0]
	v_pk_mul_f32 v[10:11], v[10:11], v[34:35] op_sel_hi:[1,0]
	v_pk_mul_f32 v[8:9], v[8:9], v[34:35] op_sel_hi:[1,0]
	v_pk_mul_f32 v[6:7], v[6:7], v[34:35] op_sel_hi:[1,0]
	v_pk_mul_f32 v[4:5], v[4:5], v[34:35] op_sel_hi:[1,0]
	v_pk_mul_f32 v[2:3], v[2:3], v[34:35] op_sel_hi:[1,0]
	v_pk_mul_f32 v[0:1], v[0:1], v[34:35] op_sel_hi:[1,0]
	v_mul_f32_e32 v153, v153, v34
	v_mov_b32_e32 v33, v32
	v_mov_b32_e32 v34, v32
	v_mov_b32_e32 v35, v32
	v_mov_b32_e32 v36, v32
	v_mov_b32_e32 v37, v32
	v_mov_b32_e32 v38, v32
	v_mov_b32_e32 v39, v32
	v_mov_b32_e32 v40, v32
	v_mov_b32_e32 v41, v32
	v_mov_b32_e32 v42, v32
	v_mov_b32_e32 v43, v32
	v_mov_b32_e32 v44, v32
	v_mov_b32_e32 v45, v32
	v_mov_b32_e32 v46, v32
	v_mov_b32_e32 v47, v32
	s_branch .LBB0_713
